# scan loop: one counted LDS wait per two MFMA steps (28 fewer issue slots per chunk)
# baseline (speedup 1.0000x reference)
; #define LAS __attribute__((address_space(3)))
; DI bf16x8 pack8(const f32x4& a, const f32x4& b) { u32x4 p; p.x = pk2(a[0], a[1]); p.y = pk2(a[2], a[3]); p.z = pk2(b[0], b[1]); p.w = pk2(b[2], b[3]); return __builtin_bit_cast(bf16x8, p); }
; #define MFMA16(a, b, c) __builtin_amdgcn_mfma_f32_16x16x32_bf16((a), (b), (c), 0, 0, 0)
; DI void scan_phase(LAS unsigned char* lds, const Args& a, int l) {
;     ...
;             for (int ks = 0; ks < 4; ++ks)
; #pragma unroll
;                 for (int m = 0; m < 4; ++m) { const bf16x8 av = *(const LAS bf16x8*)(B + O_WK + (16 * m + fr) * 272 + (32 * ks + 8 * fq) * 2); ws[m] = MFMA16(av, Sb[ks], ws[m]); }
; #pragma unroll
;             for (int ks = 0; ks < 4; ++ks)
; #pragma unroll
;                 for (int m = 0; m < 4; ++m) { const bf16x8 av = *(const LAS bf16x8*)(B + O_QD + (16 * m + fr) * 272 + (32 * ks + 8 * fq) * 2); o[m] = MFMA16(av, Sb[ks], o[m]); }
;             f32x4 u[4];
; #pragma unroll
;             for (int m = 0; m < 4; ++m) u[m] = uvc[m] - ws[m];
;             bf16x8 Ub[2]; Ub[0] = pack8(u[0], u[1]); Ub[1] = pack8(u[2], u[3]);
; #pragma unroll
;             for (int ks = 0; ks < 2; ++ks)
; #pragma unroll
;                 for (int m = 0; m < 4; ++m) { const bf16x8 av = *(const LAS bf16x8*)(B + O_QK + (16 * m + fr) * 144 + (32 * ks + 8 * fq) * 2); o[m] = MFMA16(av, Ub[ks], o[m]); }
; #pragma unroll
;             for (int mt = 0; mt < 8; ++mt) S[mt] = S[mt] * gec;
.LBB0_110:
	ds_read_b128 v[242:245], v250 offset:13120
	s_waitcnt lgkmcnt(6)
	v_mfma_f32_16x16x32_bf16 v[182:185], v[214:217], v[88:91], 0
	v_mul_f32_e32 v0, v150, v0
	v_mul_f32_e32 v1, v150, v1
	ds_read_b128 v[214:217], v250 offset:128
	v_mfma_f32_16x16x32_bf16 v[186:189], v[218:221], v[88:91], 0
	v_mul_f32_e32 v2, v150, v2
	v_mul_f32_e32 v3, v150, v3
	s_mov_b64 s[10:11], 0x4000
	v_lshl_add_u64 v[146:147], v[146:147], 0, s[10:11]
	ds_read_b128 v[218:221], v250 offset:4480
	s_waitcnt lgkmcnt(6)
	v_mfma_f32_16x16x32_bf16 v[190:193], v[222:225], v[88:91], 0
	v_mul_f32_e32 v4, v150, v4
	v_mul_f32_e32 v5, v150, v5
	ds_read_b128 v[222:225], v250 offset:8832
	v_mfma_f32_16x16x32_bf16 v[194:197], v[226:229], v[88:91], 0
	v_mul_f32_e32 v6, v150, v6
	v_mul_f32_e32 v7, v150, v7
	s_add_u32 s17, s17, 4
	s_addc_u32 s28, s28, 0
	ds_read_b128 v[226:229], v250 offset:13184
	s_waitcnt lgkmcnt(6)
	v_mfma_f32_16x16x32_bf16 v[182:185], v[230:233], v[84:87], v[182:185]
	v_mul_f32_e32 v8, v150, v8
	v_mul_f32_e32 v9, v150, v9
	ds_read_b128 v[230:233], v250 offset:192
	v_mfma_f32_16x16x32_bf16 v[186:189], v[234:237], v[84:87], v[186:189]
	v_mul_f32_e32 v10, v150, v10
	v_mul_f32_e32 v11, v150, v11
	v_lshl_add_u64 v[144:145], v[144:145], 0, s[26:27]
	ds_read_b128 v[234:237], v250 offset:4544
	s_waitcnt lgkmcnt(6)
	v_mfma_f32_16x16x32_bf16 v[190:193], v[238:241], v[84:87], v[190:193]
	v_mul_f32_e32 v12, v150, v12
	v_mul_f32_e32 v13, v150, v13
	ds_read_b128 v[238:241], v250 offset:8896
	v_mfma_f32_16x16x32_bf16 v[194:197], v[242:245], v[84:87], v[194:197]
	v_mul_f32_e32 v14, v150, v14
	v_mul_f32_e32 v15, v150, v15
	s_mov_b64 s[10:11], 0x8000
	v_lshl_add_u64 v[148:149], v[148:149], 0, s[10:11]
	ds_read_b128 v[242:245], v250 offset:13248
	s_waitcnt lgkmcnt(6)
	v_mfma_f32_16x16x32_bf16 v[182:185], v[214:217], v[80:83], v[182:185]
	v_mul_f32_e32 v16, v150, v16
	v_mul_f32_e32 v17, v150, v17
	ds_read_b128 v[214:217], v250 offset:17408
	v_mfma_f32_16x16x32_bf16 v[186:189], v[218:221], v[80:83], v[186:189]
	v_mul_f32_e32 v18, v150, v18
	v_mul_f32_e32 v19, v150, v19
	ds_read_b128 v[218:221], v250 offset:21760
	s_waitcnt lgkmcnt(6)
	v_mfma_f32_16x16x32_bf16 v[190:193], v[222:225], v[80:83], v[190:193]
	v_mul_f32_e32 v20, v150, v20
	v_mul_f32_e32 v21, v150, v21
	ds_read_b128 v[222:225], v250 offset:26112
	v_mfma_f32_16x16x32_bf16 v[194:197], v[226:229], v[80:83], v[194:197]
	v_mul_f32_e32 v22, v150, v22
	v_mul_f32_e32 v23, v150, v23
	ds_read_b128 v[226:229], v250 offset:30464
	s_waitcnt lgkmcnt(6)
	v_mfma_f32_16x16x32_bf16 v[182:185], v[230:233], v[76:79], v[182:185]
	v_mul_f32_e32 v24, v150, v24
	v_mul_f32_e32 v25, v150, v25
	ds_read_b128 v[230:233], v250 offset:17472
	v_mfma_f32_16x16x32_bf16 v[186:189], v[234:237], v[76:79], v[186:189]
	v_mul_f32_e32 v26, v150, v26
	v_mul_f32_e32 v27, v150, v27
	ds_read_b128 v[234:237], v250 offset:21824
	s_waitcnt lgkmcnt(6)
	v_mfma_f32_16x16x32_bf16 v[190:193], v[238:241], v[76:79], v[190:193]
	v_mul_f32_e32 v28, v150, v28
	v_mul_f32_e32 v29, v150, v29
	ds_read_b128 v[238:241], v250 offset:26176
	v_mfma_f32_16x16x32_bf16 v[194:197], v[242:245], v[76:79], v[194:197]
	v_mul_f32_e32 v30, v150, v30
	v_mul_f32_e32 v31, v150, v31
	ds_read_b128 v[242:245], v250 offset:30528
	s_waitcnt lgkmcnt(6)
	v_mfma_f32_16x16x32_bf16 v[198:201], v[214:217], v[88:91], 0
	ds_read_b128 v[214:217], v250 offset:17536
	v_mfma_f32_16x16x32_bf16 v[202:205], v[218:221], v[88:91], 0
	v_sub_f32_e32 v182, v104, v182
	v_sub_f32_e32 v183, v105, v183
	v_sub_f32_e32 v184, v106, v184
	v_sub_f32_e32 v185, v107, v185
	ds_read_b128 v[218:221], v250 offset:21888
	s_waitcnt lgkmcnt(6)
	v_mfma_f32_16x16x32_bf16 v[206:209], v[222:225], v[88:91], 0
	v_sub_f32_e32 v186, v96, v186
	v_sub_f32_e32 v187, v97, v187
	v_sub_f32_e32 v188, v98, v188
	v_sub_f32_e32 v189, v99, v189
	ds_read_b128 v[222:225], v250 offset:26240
	v_mfma_f32_16x16x32_bf16 v[210:213], v[226:229], v[88:91], 0
	v_sub_f32_e32 v190, v92, v190
	v_sub_f32_e32 v191, v93, v191
	v_sub_f32_e32 v192, v94, v192
	v_sub_f32_e32 v193, v95, v193
	ds_read_b128 v[226:229], v250 offset:30592
	s_waitcnt lgkmcnt(6)
	v_mfma_f32_16x16x32_bf16 v[198:201], v[230:233], v[84:87], v[198:201]
	v_sub_f32_e32 v194, v100, v194
	v_sub_f32_e32 v195, v101, v195
	v_sub_f32_e32 v196, v102, v196
	v_sub_f32_e32 v197, v103, v197
	ds_read_b128 v[230:233], v250 offset:17600
	v_mfma_f32_16x16x32_bf16 v[202:205], v[234:237], v[84:87], v[202:205]
	v_cvt_pk_bf16_f32 v246, v182, v183
	v_cvt_pk_bf16_f32 v247, v184, v185
	ds_read_b128 v[234:237], v250 offset:21952
	s_waitcnt lgkmcnt(6)
	v_mfma_f32_16x16x32_bf16 v[206:209], v[238:241], v[84:87], v[206:209]
	v_cvt_pk_bf16_f32 v248, v186, v187
	v_cvt_pk_bf16_f32 v249, v188, v189
	ds_read_b128 v[238:241], v250 offset:26304
	v_mfma_f32_16x16x32_bf16 v[210:213], v[242:245], v[84:87], v[210:213]
	v_cvt_pk_bf16_f32 v182, v190, v191
	v_cvt_pk_bf16_f32 v183, v192, v193
	ds_read_b128 v[242:245], v250 offset:30656
	s_waitcnt lgkmcnt(6)
	v_mfma_f32_16x16x32_bf16 v[198:201], v[214:217], v[80:83], v[198:201]
	v_cvt_pk_bf16_f32 v184, v194, v195
	v_cvt_pk_bf16_f32 v185, v196, v197
	ds_read_b128 v[214:217], v251 offset:34816
	v_mfma_f32_16x16x32_bf16 v[202:205], v[218:221], v[80:83], v[202:205]
	ds_read_b128 v[218:221], v251 offset:39424
	s_waitcnt lgkmcnt(6)
	v_mfma_f32_16x16x32_bf16 v[206:209], v[222:225], v[80:83], v[206:209]
	ds_read_b128 v[222:225], v251 offset:44032
	v_mfma_f32_16x16x32_bf16 v[210:213], v[226:229], v[80:83], v[210:213]
	ds_read_b128 v[226:229], v251 offset:48640
	s_waitcnt lgkmcnt(6)
; #define LAS __attribute__((address_space(3)))
; DI bf16x8 pack8(const f32x4& a, const f32x4& b) { u32x4 p; p.x = pk2(a[0], a[1]); p.y = pk2(a[2], a[3]); p.z = pk2(b[0], b[1]); p.w = pk2(b[2], b[3]); return __builtin_bit_cast(bf16x8, p); }
; #define MFMA16(a, b, c) __builtin_amdgcn_mfma_f32_16x16x32_bf16((a), (b), (c), 0, 0, 0)
; DI void scan_phase(LAS unsigned char* lds, const Args& a, int l) {
;     ...
;                 for (int m = 0; m < 4; ++m) { const bf16x8 av = *(const LAS bf16x8*)(B + O_QK + (16 * m + fr) * 144 + (32 * ks + 8 * fq) * 2); o[m] = MFMA16(av, Ub[ks], o[m]); }
; #pragma unroll
;             for (int mt = 0; mt < 8; ++mt) S[mt] = S[mt] * gec;
; #pragma unroll
;             for (int ks = 0; ks < 2; ++ks)
; #pragma unroll
;                 for (int mt = 0; mt < 8; ++mt) { const bf16x8 av = *(const LAS bf16x8*)(B + O_KET + (16 * mt + fr) * 144 + (32 * ks + 8 * fq) * 2); S[mt] = MFMA16(av, Ub[ks], S[mt]); }
; #pragma unroll
;             for (int ks = 0; ks < 4; ++ks) Sb[ks] = pack8(S[2 * ks], S[2 * ks + 1]);
;             float* op = O + (size_t)(b * 2048 + n * 64 + 4 * fq) * 512 + h * 128 + 16 * s + fr;
; #pragma unroll
;             for (int m = 0; m < 4; ++m)
; #pragma unroll
;                 for (int reg = 0; reg < 4; ++reg) op[(size_t)(16 * m + reg) * 512] = o[m][reg];
; #pragma unroll
;             for (int m = 0; m < 4; ++m) uvc[m] = uvn[m];
;             gec = gen;
;             __syncthreads();
;         }
	v_mfma_f32_16x16x32_bf16 v[198:201], v[230:233], v[76:79], v[198:201]
	ds_read_b128 v[230:233], v251 offset:34960
	v_mfma_f32_16x16x32_bf16 v[202:205], v[234:237], v[76:79], v[202:205]
	ds_read_b128 v[234:237], v251 offset:39568
	s_waitcnt lgkmcnt(6)
	v_mfma_f32_16x16x32_bf16 v[206:209], v[238:241], v[76:79], v[206:209]
	ds_read_b128 v[238:241], v251 offset:44176
	v_mfma_f32_16x16x32_bf16 v[210:213], v[242:245], v[76:79], v[210:213]
	ds_read_b128 v[242:245], v251 offset:48784
	s_waitcnt lgkmcnt(6)
	v_mfma_f32_16x16x32_bf16 v[0:3], v[214:217], v[246:249], v[0:3]
	ds_read_b128 v[214:217], v251 offset:34880
	v_mfma_f32_16x16x32_bf16 v[4:7], v[218:221], v[246:249], v[4:7]
	ds_read_b128 v[218:221], v251 offset:39488
	s_waitcnt lgkmcnt(6)
	v_mfma_f32_16x16x32_bf16 v[8:11], v[222:225], v[246:249], v[8:11]
	v_ashrrev_i32_e32 v143, 31, v142
	ds_read_b128 v[222:225], v251 offset:44096
	v_mfma_f32_16x16x32_bf16 v[12:15], v[226:229], v[246:249], v[12:15]
	ds_read_b128 v[226:229], v251 offset:48704
	s_waitcnt lgkmcnt(6)
	v_mfma_f32_16x16x32_bf16 v[16:19], v[230:233], v[246:249], v[16:19]
	v_lshlrev_b64 v[162:163], 11, v[142:143]
	ds_read_b128 v[230:233], v251 offset:35024
	v_mfma_f32_16x16x32_bf16 v[20:23], v[234:237], v[246:249], v[20:23]
	ds_read_b128 v[234:237], v251 offset:39632
	s_waitcnt lgkmcnt(6)
	v_mfma_f32_16x16x32_bf16 v[24:27], v[238:241], v[246:249], v[24:27]
	v_lshl_add_u64 v[162:163], v[140:141], 0, v[162:163]
	ds_read_b128 v[238:241], v251 offset:44240
	v_mfma_f32_16x16x32_bf16 v[28:31], v[242:245], v[246:249], v[28:31]
	ds_read_b128 v[242:245], v251 offset:48848
	s_waitcnt lgkmcnt(6)
	v_mfma_f32_16x16x32_bf16 v[0:3], v[214:217], v[182:185], v[0:3]
	v_add_u32_e32 v142, 64, v142
	ds_read_b128 v[214:217], v251 offset:53248
	v_mfma_f32_16x16x32_bf16 v[4:7], v[218:221], v[182:185], v[4:7]
	ds_read_b128 v[218:221], v251 offset:57856
	s_waitcnt lgkmcnt(6)
	v_mfma_f32_16x16x32_bf16 v[8:11], v[222:225], v[182:185], v[8:11]
	ds_read_b128 v[222:225], v251 offset:53392
	v_mfma_f32_16x16x32_bf16 v[12:15], v[226:229], v[182:185], v[12:15]
	ds_read_b128 v[226:229], v251 offset:58000
	s_waitcnt lgkmcnt(6)
	v_mfma_f32_16x16x32_bf16 v[16:19], v[230:233], v[182:185], v[16:19]
	ds_read_b128 v[230:233], v251 offset:53312
	v_mfma_f32_16x16x32_bf16 v[20:23], v[234:237], v[182:185], v[20:23]
	v_cvt_pk_bf16_f32 v88, v0, v1
	v_cvt_pk_bf16_f32 v89, v2, v3
	v_cvt_pk_bf16_f32 v90, v4, v5
	v_cvt_pk_bf16_f32 v91, v6, v7
	ds_read_b128 v[234:237], v251 offset:57920
	s_waitcnt lgkmcnt(6)
	v_mfma_f32_16x16x32_bf16 v[24:27], v[238:241], v[182:185], v[24:27]
	ds_read_b128 v[238:241], v251 offset:53456
	v_mfma_f32_16x16x32_bf16 v[28:31], v[242:245], v[182:185], v[28:31]
	v_cvt_pk_bf16_f32 v84, v8, v9
	v_cvt_pk_bf16_f32 v85, v10, v11
	v_cvt_pk_bf16_f32 v86, v12, v13
	v_cvt_pk_bf16_f32 v87, v14, v15
	ds_read_b128 v[242:245], v251 offset:58064
	s_waitcnt lgkmcnt(6)
	v_mfma_f32_16x16x32_bf16 v[198:201], v[214:217], v[246:249], v[198:201]
	v_mfma_f32_16x16x32_bf16 v[202:205], v[218:221], v[246:249], v[202:205]
	s_waitcnt lgkmcnt(4)
	v_mfma_f32_16x16x32_bf16 v[206:209], v[222:225], v[246:249], v[206:209]
	v_cvt_pk_bf16_f32 v80, v16, v17
	v_cvt_pk_bf16_f32 v81, v18, v19
	v_cvt_pk_bf16_f32 v82, v20, v21
	v_cvt_pk_bf16_f32 v83, v22, v23
	v_mfma_f32_16x16x32_bf16 v[210:213], v[226:229], v[246:249], v[210:213]
	s_waitcnt lgkmcnt(2)
	v_mfma_f32_16x16x32_bf16 v[198:201], v[230:233], v[182:185], v[198:201]
	v_mfma_f32_16x16x32_bf16 v[202:205], v[234:237], v[182:185], v[202:205]
	v_cvt_pk_bf16_f32 v76, v24, v25
	v_cvt_pk_bf16_f32 v77, v26, v27
	v_cvt_pk_bf16_f32 v78, v28, v29
	v_cvt_pk_bf16_f32 v79, v30, v31
	s_waitcnt lgkmcnt(0)
	v_mfma_f32_16x16x32_bf16 v[206:209], v[238:241], v[182:185], v[206:209]
	v_mfma_f32_16x16x32_bf16 v[210:213], v[242:245], v[182:185], v[210:213]
	s_mov_b64 s[10:11], 0x1000
	v_lshl_add_u64 v[214:215], v[162:163], 0, s[10:11]
	s_mov_b64 s[10:11], 0x9000
	v_lshl_add_u64 v[216:217], v[162:163], 0, s[10:11]
	s_mov_b64 s[10:11], 0x11000
	v_lshl_add_u64 v[218:219], v[162:163], 0, s[10:11]
	s_mov_b64 s[10:11], 0x19000
	v_lshl_add_u64 v[220:221], v[162:163], 0, s[10:11]
	s_add_i32 s9, s9, 1
	global_store_dword v[214:215], v198, off offset:-4096
	global_store_dword v[214:215], v199, off offset:-2048
	global_store_dword v[214:215], v200, off
	global_store_dword v[214:215], v201, off offset:2048
	global_store_dword v[216:217], v202, off offset:-4096
	global_store_dword v[216:217], v203, off offset:-2048
	global_store_dword v[216:217], v204, off
	global_store_dword v[216:217], v205, off offset:2048
	global_store_dword v[218:219], v206, off offset:-4096
	global_store_dword v[218:219], v207, off offset:-2048
	global_store_dword v[218:219], v208, off
	global_store_dword v[218:219], v209, off offset:2048
	global_store_dword v[220:221], v210, off offset:-4096
	global_store_dword v[220:221], v211, off offset:-2048
	global_store_dword v[220:221], v212, off
	global_store_dword v[220:221], v213, off offset:2048
	s_cmp_eq_u32 s9, 32
	s_barrier
	s_cbranch_scc1 .LBB0_106
	s_waitcnt vmcnt(16)
	v_mov_b64_e32 v[102:103], v[34:35]
	v_mov_b64_e32 v[94:95], v[38:39]
	v_mov_b64_e32 v[98:99], v[42:43]
	v_mov_b64_e32 v[106:107], v[46:47]
	v_mov_b64_e32 v[100:101], v[32:33]
	v_mov_b64_e32 v[92:93], v[36:37]
	v_mov_b64_e32 v[96:97], v[40:41]
	v_mov_b64_e32 v[104:105], v[44:45]
	v_mov_b32_e32 v150, v128
	s_branch .LBB0_108
